# convT tiles in norm phases: both tile loads issued before one wait; hyconv staging loads batched
# speedup vs baseline: 1.0373x; 1.0013x over previous
.LBB0_184:
	s_or_b64 exec, exec, s[6:7]
	s_movk_i32 s6, 0x104
	v_mad_u64_u32 v[4:5], s[6:7], v4, s6, v[8:9]
	s_waitcnt vmcnt(0)
	ds_write2_b32 v10, v52, v53 offset1:1
	ds_write2_b32 v10, v54, v55 offset0:2 offset1:3
	ds_write2_b32 v4, v0, v1 offset1:1
	ds_write2_b32 v4, v2, v3 offset0:2 offset1:3
	v_lshlrev_b32_e32 v0, 3, v9
	v_ashrrev_i32_e32 v6, 3, v9
	v_and_b32_e32 v7, 56, v0
	v_mul_u32_u24_e32 v0, 0x104, v7
	v_lshlrev_b32_e32 v1, 2, v6
	v_add3_u32 v4, 16, v0, v1
	s_waitcnt lgkmcnt(0)
	s_barrier
	ds_read2_b32 v[0:1], v4 offset1:65
	ds_read2_b32 v[2:3], v4 offset0:130 offset1:195
	v_add_u32_e32 v4, 0x400, v4
	s_waitcnt lgkmcnt(1)
	v_cvt_pk_bf16_f32 v0, v0, v1
	s_waitcnt lgkmcnt(0)
	v_cvt_pk_bf16_f32 v1, v2, v3
	ds_read2_b32 v[2:3], v4 offset0:4 offset1:69
	ds_read2_b32 v[4:5], v4 offset0:134 offset1:199
	s_mulk_i32 s5, 0x2c00
	s_waitcnt lgkmcnt(1)
	v_cvt_pk_bf16_f32 v2, v2, v3
	s_waitcnt lgkmcnt(0)
	v_cvt_pk_bf16_f32 v3, v4, v5
	v_subrev_u32_e32 v4, s5, v6
	v_add_u32_e32 v4, s10, v4
	v_ashrrev_i32_e32 v5, 31, v4
	v_lshlrev_b64 v[4:5], 12, v[4:5]
	v_lshl_add_u64 v[4:5], s[2:3], 0, v[4:5]
	s_ashr_i32 s5, s4, 31
	v_lshl_add_u64 v[4:5], s[4:5], 1, v[4:5]
	v_lshlrev_b32_e32 v32, 1, v7
	v_lshl_add_u64 v[4:5], v[4:5], 0, v[32:33]
	flat_store_dwordx4 v[4:5], v[0:3]
	s_waitcnt lgkmcnt(0)
	s_barrier

.LBB0_186:
	s_cmpk_gt_i32 s11, 0x15ff
	s_mov_b64 s[4:5], -1
	s_cbranch_scc0 .LBB0_188
	v_mov_b32_e32 v10, v224
	s_and_b32 s7, s10, 0x7c0
	s_and_b32 s6, s9, 0x1ffc0
	v_lshlrev_b32_e32 v0, 4, v10
	s_lshl_b32 s4, s7, 2
	v_readlane_b32 s5, v254, 19
	v_ashrrev_i32_e32 v2, 4, v10
	v_and_b32_e32 v32, 0xf0, v0
	s_add_u32 s4, s5, s4
	v_readlane_b32 s5, v254, 20
	v_add_u32_e32 v0, s6, v2
	s_addc_u32 s5, s5, 0
	v_ashrrev_i32_e32 v1, 31, v0
	v_lshl_add_u64 v[6:7], s[4:5], 0, v[32:33]
	v_lshlrev_b64 v[0:1], 13, v[0:1]
	v_add_u32_e32 v4, 16, v32
	v_lshl_add_u64 v[0:1], v[6:7], 0, v[0:1]
	s_movk_i32 s12, 0x104
	v_mad_u64_u32 v[8:9], s[4:5], v2, s12, v[4:5]
	global_load_dwordx4 v[52:55], v[0:1], off
	s_lshl_b32 s66, s6, 1
	v_add_u32_e32 v0, 0x200, v10
	v_ashrrev_i32_e32 v2, 4, v0
	v_add_u32_e32 v0, s6, v2
	v_ashrrev_i32_e32 v1, 31, v0
	v_lshlrev_b64 v[0:1], 13, v[0:1]
	v_lshl_add_u64 v[0:1], v[6:7], 0, v[0:1]
	v_mad_u64_u32 v[4:5], s[4:5], v2, s12, v[4:5]
	global_load_dwordx4 v[0:3], v[0:1], off
	v_ashrrev_i32_e32 v6, 3, v10
	s_movk_i32 s4, 0x2c00
	s_waitcnt vmcnt(0)
	ds_write2_b32 v8, v52, v53 offset1:1
	ds_write2_b32 v8, v54, v55 offset0:2 offset1:3
	ds_write2_b32 v4, v0, v1 offset1:1
	ds_write2_b32 v4, v2, v3 offset0:2 offset1:3
	v_lshlrev_b32_e32 v0, 3, v10
	v_and_b32_e32 v7, 56, v0
	v_mul_u32_u24_e32 v0, 0x104, v7
	v_lshlrev_b32_e32 v1, 2, v6
	v_add3_u32 v4, 16, v0, v1
	s_waitcnt lgkmcnt(0)
	s_barrier
	ds_read2_b32 v[0:1], v4 offset1:65
	ds_read2_b32 v[2:3], v4 offset0:130 offset1:195
	v_add_u32_e32 v4, 0x400, v4
	s_waitcnt lgkmcnt(1)
	v_cvt_pk_bf16_f32 v0, v0, v1
	s_waitcnt lgkmcnt(0)
	v_cvt_pk_bf16_f32 v1, v2, v3
	ds_read2_b32 v[2:3], v4 offset0:4 offset1:69
	ds_read2_b32 v[4:5], v4 offset0:134 offset1:199
	s_waitcnt lgkmcnt(1)
	v_cvt_pk_bf16_f32 v2, v2, v3
	s_waitcnt lgkmcnt(0)
	v_cvt_pk_bf16_f32 v3, v4, v5
	v_add_u32_e32 v6, s7, v6
	v_mov_b64_e32 v[4:5], s[0:1]
	v_mad_i64_i32 v[4:5], s[4:5], v6, s4, v[4:5]
	v_lshl_add_u64 v[4:5], v[4:5], 0, s[66:67]
	v_lshlrev_b32_e32 v32, 1, v7
	v_lshl_add_u64 v[4:5], v[4:5], 0, v[32:33]
	flat_store_dwordx4 v[4:5], v[0:3]
	s_waitcnt lgkmcnt(0)
	s_barrier
	s_mov_b64 s[4:5], 0
.LBB0_188:
	s_andn2_b64 vcc, exec, s[4:5]
	s_cbranch_vccnz .LBB0_185
	s_mul_hi_i32 s4, s11, 0x2e8ba2e9
	s_lshr_b32 s5, s4, 31
	s_ashr_i32 s4, s4, 5
	v_mov_b32_e32 v9, v224
	s_add_i32 s5, s4, s5
	s_mul_i32 s6, s5, 0xffffd400
	v_lshlrev_b32_e32 v0, 2, v9
	s_add_i32 s6, s10, s6
	v_and_b32_e32 v1, 60, v0
	v_add_u32_e32 v0, s6, v1
	s_movk_i32 s7, 0x2c00
	v_cmp_gt_i32_e32 vcc, s7, v0
	s_ashr_i32 s7, s6, 31
	s_lshl_b32 s4, s5, 6
	s_lshl_b64 s[6:7], s[6:7], 2
	v_readlane_b32 s12, v254, 21
	s_add_u32 s6, s12, s6
	v_readlane_b32 s12, v254, 22
	s_addc_u32 s7, s12, s7
	v_lshlrev_b32_e32 v32, 2, v1
	v_lshl_add_u64 v[6:7], s[6:7], 0, v[32:33]
	v_ashrrev_i32_e32 v10, 4, v9
	v_mov_b32_e32 v0, 0
	v_mov_b32_e32 v2, 0
	v_mov_b32_e32 v3, 0
	v_mov_b32_e32 v4, 0
	v_mov_b32_e32 v5, 0
	v_mov_b32_e32 v52, 0
	v_mov_b32_e32 v53, 0
	v_mov_b32_e32 v54, 0
	v_mov_b32_e32 v55, 0
	s_and_saveexec_b64 s[6:7], vcc
	s_cbranch_execz .LBB0_191
	v_add_u32_e32 v2, s4, v10
	s_mov_b32 s12, 0xb000
	v_mad_i64_i32 v[2:3], s[12:13], v2, s12, v[6:7]
	global_load_dwordx4 v[52:55], v[2:3], off
.LBB0_191:
	s_or_b64 exec, exec, s[6:7]
	v_lshl_add_u32 v8, v1, 2, 16
	s_movk_i32 s6, 0x104
	v_mad_u64_u32 v[10:11], s[6:7], v10, s6, v[8:9]
	v_add_u32_e32 v1, 0x200, v9
	v_ashrrev_i32_e32 v4, 4, v1
	v_mov_b32_e32 v1, 0
	v_mov_b32_e32 v2, 0
	v_mov_b32_e32 v3, 0
	s_and_saveexec_b64 s[6:7], vcc
	s_cbranch_execz .LBB0_184
	v_add_u32_e32 v0, s4, v4
	s_mov_b32 s12, 0xb000
	v_mad_i64_i32 v[0:1], s[12:13], v0, s12, v[6:7]
	global_load_dwordx4 v[0:3], v[0:1], off
	s_branch .LBB0_184

.LBB0_725:
	s_or_b64 exec, exec, s[0:1]
	s_mov_b64 s[0:1], src_shared_base
	s_cmp_lg_u32 16, -1
	s_cselect_b32 s0, s1, 0
	s_cselect_b32 s1, 16, 0
	v_mov_b32_e32 v0, s1
	v_mov_b32_e32 v1, s0
	s_waitcnt lgkmcnt(0)
	s_barrier
	flat_load_dword v78, v[0:1] sc0 sc1
	s_waitcnt vmcnt(0)
	s_movk_i32 s0, 0xc00
	s_waitcnt lgkmcnt(0)
	s_barrier
	v_cmp_gt_u32_e32 vcc, s0, v78
	s_mov_b64 s[0:1], -1
	s_and_saveexec_b64 s[64:65], vcc
	s_cbranch_execz .LBB0_722
	s_movk_i32 s0, 0x3ff
	v_cmp_lt_u32_e32 vcc, s0, v78
	s_and_saveexec_b64 s[0:1], vcc
	s_xor_b64 s[2:3], exec, s[0:1]
	s_cbranch_execz .LBB0_748
	v_add_u32_e32 v1, 0xfffffc00, v78
	s_movk_i32 s0, 0x400
	v_add_u32_e32 v0, 0xfffff800, v78
	v_cmp_gt_u32_e32 vcc, s0, v1
	v_mov_b32_e32 v3, 0x100
	v_mov_b32_e32 v4, 0x4000
	v_cndmask_b32_e32 v2, v0, v1, vcc
	v_cndmask_b32_e32 v45, v3, v231, vcc
	v_mov_b32_e32 v3, 0x2000
	s_movk_i32 s0, 0x6000
	v_cndmask_b32_e32 v3, v3, v4, vcc
	v_cndmask_b32_e32 v32, 0, v4, vcc
	v_mul_lo_u32 v4, v2, s0
	v_mov_b32_e32 v5, v33
	v_mov_b32_e32 v34, v224
	v_lshl_add_u64 v[4:5], v[4:5], 1, s[22:23]
	v_lshl_add_u64 v[42:43], v[4:5], 0, v[32:33]
	v_lshlrev_b32_e32 v4, 3, v34
	v_lshlrev_b32_e32 v35, 1, v45
	v_cmp_lt_i32_e64 s[0:1], v4, v3
	s_and_saveexec_b64 s[4:5], s[0:1]
	s_cbranch_execz .LBB0_730
	s_mov_b64 s[0:1], 0x2000
	v_lshlrev_b32_e32 v12, 1, v4
	v_mov_b32_e32 v13, v33
	v_lshl_add_u64 v[12:13], v[42:43], 0, v[12:13]
	global_load_dwordx4 v[16:19], v[12:13], off
	v_lshl_add_u64 v[12:13], v[12:13], 0, s[0:1]
	global_load_dwordx4 v[20:23], v[12:13], off
	s_cbranch_vccz .Lhyc_a1
	v_lshl_add_u64 v[12:13], v[12:13], 0, s[0:1]
	global_load_dwordx4 v[24:27], v[12:13], off
	v_lshl_add_u64 v[12:13], v[12:13], 0, s[0:1]
	global_load_dwordx4 v[28:31], v[12:13], off
.Lhyc_a1:
	v_mov_b32_e32 v9, 8
	v_mov_b32_e32 v10, 12
	v_cndmask_b32_e32 v5, v9, v10, vcc
	v_mov_b32_e32 v9, 0x2100
	v_mov_b32_e32 v10, 0x2010
	v_lshrrev_b32_e32 v6, v5, v4
	v_lshlrev_b32_e32 v7, 1, v4
	v_lshl_add_u32 v6, v6, 4, v7
	v_cndmask_b32_e32 v7, v9, v10, vcc
	v_add_u32_e32 v6, 16, v6
	s_waitcnt vmcnt(0)
	ds_write_b128 v6, v[16:19]
	v_add_u32_e32 v6, v6, v7
	ds_write_b128 v6, v[20:23]
	s_cbranch_vccz .Lhyc_a2
	v_add_u32_e32 v6, v6, v7
	ds_write_b128 v6, v[24:27]
	v_add_u32_e32 v6, v6, v7
	ds_write_b128 v6, v[28:31]
.Lhyc_a2:
.LBB0_730:
	s_or_b64 exec, exec, s[4:5]
	v_cndmask_b32_e64 v8, 5, 2, vcc
	v_or_b32_e32 v36, 8, v45
	v_lshlrev_b32_e32 v37, v8, v36
	v_cmp_lt_i32_e64 s[0:1], v4, v35
	s_and_saveexec_b64 s[4:5], s[0:1]
	s_cbranch_execz .LBB0_735
	v_lshlrev_b32_e32 v32, 14, v1
	v_mov_b32_e32 v1, v33
	v_lshlrev_b64 v[0:1], 10, v[0:1]
	v_lshl_add_u64 v[2:3], s[20:21], 0, v[32:33]
	v_lshl_add_u64 v[0:1], s[56:57], 0, v[0:1]
	v_cndmask_b32_e32 v1, v1, v3, vcc
	v_cndmask_b32_e32 v0, v0, v2, vcc
	v_lshlrev_b32_e32 v2, 4, v34
	v_lshlrev_b32_e32 v3, 1, v37
	v_ashrrev_i32_e32 v5, 31, v4
	v_add_u32_e32 v9, -8, v35
	v_lshlrev_b32_e32 v10, 2, v45
	v_add3_u32 v11, v2, v3, 16
	v_lshl_add_u64 v[6:7], v[4:5], 1, v[0:1]
	s_mov_b64 s[0:1], 0x2000
	v_mov_b32_e32 v24, 0
	v_mov_b32_e32 v25, 0
	global_load_dwordx4 v[16:19], v[6:7], off
	v_cmp_lt_i32_e64 s[6:7], v4, v9
	s_and_saveexec_b64 s[8:9], s[6:7]
	global_load_ushort v24, v[6:7], off offset:16
	s_mov_b64 exec, s[8:9]
	s_cbranch_vccz .Lhyc_b1
	v_lshl_add_u64 v[12:13], v[6:7], 0, s[0:1]
	global_load_dwordx4 v[20:23], v[12:13], off
	v_add_u32_e32 v14, 0x1000, v4
	v_cmp_lt_i32_e64 s[6:7], v14, v9
	s_and_saveexec_b64 s[8:9], s[6:7]
	global_load_ushort v25, v[12:13], off offset:16
	s_mov_b64 exec, s[8:9]
.Lhyc_b1:
	s_mov_b32 s0, 0x1000706
	s_waitcnt vmcnt(0)
	ds_write_b128 v11, v[16:19]
	v_lshlrev_b32_e32 v24, 16, v24
	v_perm_b32 v16, v16, v17, s0
	v_perm_b32 v17, v17, v18, s0
	v_perm_b32 v18, v18, v19, s0
	v_or_b32_sdwa v19, v24, v19 dst_sel:DWORD dst_unused:UNUSED_PAD src0_sel:DWORD src1_sel:WORD_1
	v_add_u32_e32 v5, v11, v10
	ds_write_b128 v5, v[16:19]
	s_cbranch_vccz .Lhyc_b2
	v_add_u32_e32 v11, 0x2000, v11
	ds_write_b128 v11, v[20:23]
	v_lshlrev_b32_e32 v25, 16, v25
	v_perm_b32 v20, v20, v21, s0
	v_perm_b32 v21, v21, v22, s0
	v_perm_b32 v22, v22, v23, s0
	v_or_b32_sdwa v23, v25, v23 dst_sel:DWORD dst_unused:UNUSED_PAD src0_sel:DWORD src1_sel:WORD_1
	v_add_u32_e32 v5, v11, v10
	ds_write_b128 v5, v[20:23]
.Lhyc_b2:
.LBB0_735:
	s_or_b64 exec, exec, s[4:5]
	v_ashrrev_i32_e32 v0, 6, v34
	v_cndmask_b32_e64 v1, 0, 1, vcc
	v_lshlrev_b32_e32 v0, v1, v0
	v_and_b32_e32 v47, 31, v34
	v_lshlrev_b32_e32 v2, 5, v0
	v_add_u32_e32 v0, v0, v1
	v_or_b32_e32 v3, v2, v47
	v_ashrrev_i32_e32 v41, v8, v2
	v_lshl_or_b32 v0, v0, 5, 31
	v_mov_b32_e32 v1, 0xffffff10
	v_mov_b32_e32 v2, 0xfffff010
	v_add_u32_e32 v4, 32, v3
	v_lshlrev_b32_e32 v38, 5, v41
	v_cndmask_b32_e32 v40, v1, v2, vcc
	v_ashrrev_i32_e32 v0, v8, v0
	v_ashrrev_i32_e32 v39, v8, v3
	v_add_u32_e32 v1, v38, v40
	v_cndmask_b32_e64 v2, 31, 3, vcc
	v_ashrrev_i32_e32 v50, v8, v4
	v_lshlrev_b32_e32 v32, 5, v0
	v_mov_b32_e32 v31, 0
	v_bfe_u32 v48, v34, 5, 1
	v_lshlrev_b32_e32 v46, 5, v39
	v_and_b32_e32 v49, v34, v2
	v_lshlrev_b32_e32 v44, 5, v50
	v_cmp_le_i32_e64 s[0:1], v1, v32
	v_mov_b32_e32 v30, v31
	v_mov_b32_e32 v29, v31
	v_mov_b32_e32 v28, v31
	v_mov_b32_e32 v27, v31
	v_mov_b32_e32 v26, v31
	v_mov_b32_e32 v25, v31
	v_mov_b32_e32 v24, v31
	v_mov_b32_e32 v23, v31
	v_mov_b32_e32 v22, v31
	v_mov_b32_e32 v21, v31
	v_mov_b32_e32 v20, v31
	v_mov_b32_e32 v19, v31
	v_mov_b32_e32 v18, v31
	v_mov_b32_e32 v17, v31
	v_mov_b32_e32 v16, v31
	v_mov_b32_e32 v15, v31
	v_mov_b32_e32 v14, v31
	v_mov_b32_e32 v13, v31
	v_mov_b32_e32 v12, v31
	v_mov_b32_e32 v11, v31
	v_mov_b32_e32 v10, v31
	v_mov_b32_e32 v9, v31
	v_mov_b32_e32 v8, v31
	v_mov_b32_e32 v7, v31
	v_mov_b32_e32 v6, v31
	v_mov_b32_e32 v5, v31
	v_mov_b32_e32 v4, v31
	v_mov_b32_e32 v3, v31
	v_mov_b32_e32 v2, v31
	v_mov_b32_e32 v1, v31
	v_mov_b32_e32 v0, v31
	s_waitcnt lgkmcnt(0)
	s_barrier
	s_and_saveexec_b64 s[4:5], s[0:1]
	s_cbranch_execz .LBB0_745
	v_lshl_add_u32 v0, v37, 1, 16
	v_and_b32_e32 v3, 1, v34
	v_lshl_add_u32 v1, v35, 1, v0
	v_mul_u32_u24_e32 v2, v49, v36
	v_cmp_eq_u32_e64 s[0:1], 0, v3
	v_lshlrev_b32_e32 v3, 4, v48
	v_lshl_or_b32 v4, v50, 6, v3
	v_cndmask_b32_e64 v0, v1, v0, s[0:1]
	v_sub_u32_e32 v1, v45, v47
	v_lshlrev_b32_e32 v2, 1, v2
	v_lshl_or_b32 v3, v39, 6, v3
	v_lshl_add_u32 v1, v48, 3, v1
	v_add_u32_e32 v4, v4, v2
	v_lshlrev_b32_e32 v5, 1, v40
	v_add_u32_e32 v2, v3, v2
	v_and_b32_e32 v1, 0x3ffe, v1
	v_sub_u32_e32 v4, v4, v5
	v_lshlrev_b32_e32 v6, 6, v41
	v_sub_u32_e32 v2, v2, v5
	v_sub_u32_e32 v4, v4, v6
	v_sub_u32_e32 v2, v2, v6
	v_sub_u32_e32 v1, v1, v40
	v_add_u32_e32 v50, 16, v4
	v_sub_u32_e32 v4, v44, v40
	v_add_u32_e32 v52, 16, v2
	v_sub_u32_e32 v2, v46, v40
	v_sub_u32_e32 v1, v1, v38
	v_mov_b32_e32 v16, 0
	s_mov_b32 s12, 0
	v_add3_u32 v47, v40, v38, -16
	v_sub_u32_e32 v51, v4, v38
	v_sub_u32_e32 v53, v2, v38
	v_lshl_add_u32 v54, v1, 1, v0
	s_mov_b64 s[6:7], 0
	v_mov_b32_e32 v17, v16
	v_mov_b32_e32 v18, v16
	v_mov_b32_e32 v19, v16
	v_mov_b32_e32 v20, v16
	v_mov_b32_e32 v21, v16
	v_mov_b32_e32 v22, v16
	v_mov_b32_e32 v23, v16
	v_mov_b32_e32 v24, v16
	v_mov_b32_e32 v25, v16
	v_mov_b32_e32 v26, v16
	v_mov_b32_e32 v27, v16
	v_mov_b32_e32 v28, v16
	v_mov_b32_e32 v29, v16
	v_mov_b32_e32 v30, v16
	v_mov_b32_e32 v31, v16
	v_mov_b32_e32 v0, v16
	v_mov_b32_e32 v1, v16
	v_mov_b32_e32 v2, v16
	v_mov_b32_e32 v3, v16
	v_mov_b32_e32 v4, v16
	v_mov_b32_e32 v5, v16
	v_mov_b32_e32 v6, v16
	v_mov_b32_e32 v7, v16
	v_mov_b32_e32 v8, v16
	v_mov_b32_e32 v9, v16
	v_mov_b32_e32 v10, v16
	v_mov_b32_e32 v11, v16
	v_mov_b32_e32 v12, v16
	v_mov_b32_e32 v13, v16
	v_mov_b32_e32 v14, v16
	v_mov_b32_e32 v15, v16
	s_branch .LBB0_739

.LBB0_1044:
	s_or_b64 exec, exec, s[6:7]
	s_movk_i32 s6, 0x104
	v_mad_u64_u32 v[4:5], s[6:7], v4, s6, v[8:9]
	s_waitcnt vmcnt(0)
	ds_write2_b32 v10, v52, v53 offset1:1
	ds_write2_b32 v10, v54, v55 offset0:2 offset1:3
	ds_write2_b32 v4, v0, v1 offset1:1
	ds_write2_b32 v4, v2, v3 offset0:2 offset1:3
	v_lshlrev_b32_e32 v0, 3, v9
	v_ashrrev_i32_e32 v6, 3, v9
	v_and_b32_e32 v7, 56, v0
	v_mul_u32_u24_e32 v0, 0x104, v7
	v_lshlrev_b32_e32 v1, 2, v6
	v_add3_u32 v4, 16, v0, v1
	s_waitcnt lgkmcnt(0)
	s_barrier
	ds_read2_b32 v[0:1], v4 offset1:65
	ds_read2_b32 v[2:3], v4 offset0:130 offset1:195
	v_add_u32_e32 v4, 0x400, v4
	s_waitcnt lgkmcnt(1)
	v_cvt_pk_bf16_f32 v0, v0, v1
	s_waitcnt lgkmcnt(0)
	v_cvt_pk_bf16_f32 v1, v2, v3
	ds_read2_b32 v[2:3], v4 offset0:4 offset1:69
	ds_read2_b32 v[4:5], v4 offset0:134 offset1:199
	s_mulk_i32 s3, 0x1900
	s_waitcnt lgkmcnt(1)
	v_cvt_pk_bf16_f32 v2, v2, v3
	s_waitcnt lgkmcnt(0)
	v_cvt_pk_bf16_f32 v3, v4, v5
	v_subrev_u32_e32 v4, s3, v6
	v_add_u32_e32 v4, s10, v4
	v_ashrrev_i32_e32 v5, 31, v4
	v_lshlrev_b64 v[4:5], 12, v[4:5]
	v_lshl_add_u64 v[4:5], s[0:1], 0, v[4:5]
	s_ashr_i32 s3, s2, 31
	v_lshl_add_u64 v[4:5], s[2:3], 1, v[4:5]
	v_lshlrev_b32_e32 v32, 1, v7
	v_lshl_add_u64 v[4:5], v[4:5], 0, v[32:33]
	v_readlane_b32 s24, v253, 6
	v_readlane_b32 s25, v255, 22
	flat_store_dwordx4 v[4:5], v[0:3]
	s_waitcnt lgkmcnt(0)
	s_barrier

.LBB0_1046:
	s_cmpk_gt_i32 s11, 0xc7f
	s_mov_b64 s[2:3], -1
	s_cbranch_scc0 .LBB0_1048
	v_mov_b32_e32 v10, v224
	s_and_b32 s7, s10, 0x7c0
	v_readlane_b32 s12, v254, 0
	s_and_b32 s6, s9, 0x1ffc0
	v_lshlrev_b32_e32 v0, 4, v10
	s_lshl_b32 s2, s7, 2
	v_readlane_b32 s22, v254, 10
	v_ashrrev_i32_e32 v2, 4, v10
	v_and_b32_e32 v32, 0xf0, v0
	v_readlane_b32 s23, v254, 11
	s_add_u32 s2, s22, s2
	v_add_u32_e32 v0, s6, v2
	s_addc_u32 s3, s23, 0
	v_ashrrev_i32_e32 v1, 31, v0
	v_lshl_add_u64 v[6:7], s[2:3], 0, v[32:33]
	v_lshlrev_b64 v[0:1], 13, v[0:1]
	v_add_u32_e32 v4, 16, v32
	v_lshl_add_u64 v[0:1], v[6:7], 0, v[0:1]
	s_movk_i32 s12, 0x104
	v_mad_u64_u32 v[8:9], s[2:3], v2, s12, v[4:5]
	global_load_dwordx4 v[52:55], v[0:1], off
	s_lshl_b32 s66, s6, 1
	v_readlane_b32 s24, v254, 12
	v_readlane_b32 s25, v254, 13
	v_readlane_b32 s13, v254, 1
	v_readlane_b32 s14, v254, 2
	v_readlane_b32 s15, v254, 3
	v_readlane_b32 s16, v254, 4
	v_readlane_b32 s17, v254, 5
	v_readlane_b32 s18, v254, 6
	v_readlane_b32 s19, v254, 7
	v_readlane_b32 s20, v254, 8
	v_readlane_b32 s21, v254, 9
	v_readlane_b32 s26, v254, 14
	v_readlane_b32 s27, v254, 15
	v_readlane_b32 s25, v255, 22
	v_readlane_b32 s24, v253, 6
	v_add_u32_e32 v0, 0x200, v10
	v_ashrrev_i32_e32 v2, 4, v0
	v_add_u32_e32 v0, s6, v2
	v_ashrrev_i32_e32 v1, 31, v0
	v_lshlrev_b64 v[0:1], 13, v[0:1]
	v_lshl_add_u64 v[0:1], v[6:7], 0, v[0:1]
	v_mad_u64_u32 v[4:5], s[2:3], v2, s12, v[4:5]
	global_load_dwordx4 v[0:3], v[0:1], off
	v_ashrrev_i32_e32 v6, 3, v10
	s_mov_b64 s[2:3], 0
	s_waitcnt vmcnt(0)
	ds_write2_b32 v8, v52, v53 offset1:1
	ds_write2_b32 v8, v54, v55 offset0:2 offset1:3
	ds_write2_b32 v4, v0, v1 offset1:1
	ds_write2_b32 v4, v2, v3 offset0:2 offset1:3
	v_lshlrev_b32_e32 v0, 3, v10
	v_and_b32_e32 v7, 56, v0
	v_mul_u32_u24_e32 v0, 0x104, v7
	v_lshlrev_b32_e32 v1, 2, v6
	v_add3_u32 v4, 16, v0, v1
	s_waitcnt lgkmcnt(0)
	s_barrier
	ds_read2_b32 v[0:1], v4 offset1:65
	ds_read2_b32 v[2:3], v4 offset0:130 offset1:195
	v_add_u32_e32 v4, 0x400, v4
	s_waitcnt lgkmcnt(1)
	v_cvt_pk_bf16_f32 v0, v0, v1
	s_waitcnt lgkmcnt(0)
	v_cvt_pk_bf16_f32 v1, v2, v3
	ds_read2_b32 v[2:3], v4 offset0:4 offset1:69
	ds_read2_b32 v[4:5], v4 offset0:134 offset1:199
	s_waitcnt lgkmcnt(1)
	v_cvt_pk_bf16_f32 v2, v2, v3
	s_waitcnt lgkmcnt(0)
	v_cvt_pk_bf16_f32 v3, v4, v5
	v_add_u32_e32 v4, s7, v6
	v_ashrrev_i32_e32 v5, 31, v4
	v_lshlrev_b64 v[4:5], 12, v[4:5]
	v_lshl_add_u64 v[4:5], s[4:5], 0, v[4:5]
	v_lshl_add_u64 v[4:5], v[4:5], 0, s[66:67]
	v_lshlrev_b32_e32 v32, 1, v7
	v_lshl_add_u64 v[4:5], v[4:5], 0, v[32:33]
	flat_store_dwordx4 v[4:5], v[0:3]
	s_waitcnt lgkmcnt(0)
	s_barrier
.LBB0_1048:
	s_andn2_b64 vcc, exec, s[2:3]
	s_cbranch_vccnz .LBB0_1045
	s_mul_hi_i32 s2, s11, 0x51eb851f
	s_lshr_b32 s3, s2, 31
	s_ashr_i32 s2, s2, 5
	v_mov_b32_e32 v9, v224
	s_add_i32 s3, s2, s3
	s_mul_i32 s6, s3, 0xffffe700
	v_lshlrev_b32_e32 v0, 2, v9
	s_add_i32 s6, s10, s6
	v_and_b32_e32 v1, 60, v0
	v_add_u32_e32 v0, s6, v1
	s_movk_i32 s7, 0x1820
	v_cmp_gt_i32_e32 vcc, s7, v0
	s_ashr_i32 s7, s6, 31
	v_readlane_b32 s12, v254, 0
	s_lshl_b32 s2, s3, 6
	s_lshl_b64 s[6:7], s[6:7], 2
	v_readlane_b32 s20, v254, 8
	v_readlane_b32 s21, v254, 9
	s_add_u32 s6, s20, s6
	s_addc_u32 s7, s21, s7
	v_lshlrev_b32_e32 v32, 2, v1
	v_lshl_add_u64 v[6:7], s[6:7], 0, v[32:33]
	v_ashrrev_i32_e32 v10, 4, v9
	v_mov_b32_e32 v0, 0
	v_mov_b32_e32 v2, 0
	v_mov_b32_e32 v3, 0
	v_mov_b32_e32 v4, 0
	v_mov_b32_e32 v5, 0
	v_readlane_b32 s13, v254, 1
	v_readlane_b32 s14, v254, 2
	v_readlane_b32 s15, v254, 3
	v_readlane_b32 s16, v254, 4
	v_readlane_b32 s17, v254, 5
	v_readlane_b32 s18, v254, 6
	v_readlane_b32 s19, v254, 7
	v_readlane_b32 s22, v254, 10
	v_readlane_b32 s23, v254, 11
	v_readlane_b32 s24, v254, 12
	v_readlane_b32 s25, v254, 13
	v_readlane_b32 s26, v254, 14
	v_readlane_b32 s27, v254, 15
	v_mov_b32_e32 v52, 0
	v_mov_b32_e32 v53, 0
	v_mov_b32_e32 v54, 0
	v_mov_b32_e32 v55, 0
	s_and_saveexec_b64 s[6:7], vcc
	s_cbranch_execz .LBB0_1051
	v_add_u32_e32 v2, s2, v10
	s_movk_i32 s12, 0x6080
	v_mad_i64_i32 v[2:3], s[12:13], v2, s12, v[6:7]
	global_load_dwordx4 v[52:55], v[2:3], off
.LBB0_1051:
	s_or_b64 exec, exec, s[6:7]
	v_lshl_add_u32 v8, v1, 2, 16
	s_movk_i32 s6, 0x104
	v_mad_u64_u32 v[10:11], s[6:7], v10, s6, v[8:9]
	v_add_u32_e32 v1, 0x200, v9
	v_ashrrev_i32_e32 v4, 4, v1
	v_mov_b32_e32 v1, 0
	v_mov_b32_e32 v2, 0
	v_mov_b32_e32 v3, 0
	s_and_saveexec_b64 s[6:7], vcc
	s_cbranch_execz .LBB0_1044
	v_add_u32_e32 v0, s2, v4
	s_movk_i32 s12, 0x6080
	v_mad_i64_i32 v[0:1], s[12:13], v0, s12, v[6:7]
	global_load_dwordx4 v[0:3], v[0:1], off
	s_branch .LBB0_1044
